# prep LoRA up-projections via v_mfma_f32_16x16x32_bf16 (replaces 128 v_dot2c per token pair); LDS +3KB transpose scratch
# speedup vs baseline: 1.0234x; 1.0234x over previous
; __device__ void scan_chain(PRef p, int l, int chain, ScanSm* sm) {
;     ...
;     PrepConst pc;
;     int hc = h * 64 + lane;
;     pc.cols[0] = hc; pc.cols[1] = 512 + hc; pc.cols[2] = 1024 + hc; pc.cols[3] = 1536 + d * 64 + lane; pc.cols[4] = 1664 + d * 64 + lane;
; #pragma unroll
;     for (int i = 0; i < 5; i++) { pc.mup[i] = p.a_mu_prev[l * 1792 + pc.cols[i]]; pc.mun[i] = p.a_mu_next[l * 1792 + pc.cols[i]]; }
;     pc.w0v = p.a_w0[l * 1024 + d * 512 + hc];
;     pc.a0v = p.a_a0[l * 1024 + d * 512 + hc];
;     pc.kkc = p.a_k_k[l * 512 + hc];
;     pc.kac = p.a_k_a[l * 512 + hc];
;     pc.rkc = p.a_r_k[l * 512 + hc];
;     {
;       const float* wu = p.a_w_up + ((size_t)(l * 2 + d) * 64) * 512 + hc;
;       const float* au = p.a_a_up + ((size_t)(l * 2 + d) * 64) * 512 + hc;
; #pragma unroll
;       for (int r = 0; r < 32; r++) {
;         pc.wu[r] = pack2(wu[(2 * r) * 512], wu[(2 * r + 1) * 512]);
;         pc.au[r] = pack2(au[(2 * r) * 512], au[(2 * r + 1) * 512]);
;       }
;     }
.LBB0_567:
	s_or_b64 exec, exec, s[6:7]
	s_ashr_i32 s28, s56, 4
	s_bfe_u32 s63, s56, 0x30001
	s_and_b32 s62, s56, 1
	s_waitcnt lgkmcnt(0)
	s_barrier
	s_setprio 3
	s_mulk_i32 s28, 0x900
	s_and_saveexec_b64 s[0:1], vcc
	s_xor_b64 s[20:21], exec, s[0:1]
	s_cbranch_execz .LBB0_606
	v_lshl_or_b32 v7, s63, 6, v28
	v_add_u32_e32 v0, s57, v7
	v_ashrrev_i32_e32 v1, 31, v0
	v_lshlrev_b64 v[4:5], 2, v[0:1]
	v_add_u32_e32 v0, 0x400, v0
	v_ashrrev_i32_e32 v1, 31, v0
	v_lshl_or_b32 v6, s62, 6, v28
	v_lshl_add_u64 v[8:9], s[36:37], 0, v[4:5]
	v_lshl_add_u64 v[4:5], s[38:39], 0, v[4:5]
	v_lshlrev_b64 v[0:1], 2, v[0:1]
	global_load_dword v14, v[8:9], off
	global_load_dword v15, v[8:9], off offset:2048
	global_load_dword v16, v[4:5], off
	global_load_dword v17, v[4:5], off offset:2048
	v_lshl_add_u64 v[4:5], s[36:37], 0, v[0:1]
	v_lshl_add_u64 v[0:1], s[38:39], 0, v[0:1]
	v_add_u32_e32 v2, s57, v6
	global_load_dword v19, v[0:1], off
	v_add_u32_e32 v0, 0x600, v2
	v_ashrrev_i32_e32 v1, 31, v0
	v_lshlrev_b64 v[0:1], 2, v[0:1]
	global_load_dword v18, v[4:5], off
	v_lshl_add_u64 v[4:5], s[36:37], 0, v[0:1]
	v_lshl_add_u64 v[0:1], s[38:39], 0, v[0:1]
	global_load_dword v21, v[0:1], off
	v_add_u32_e32 v0, 0x680, v2
	v_ashrrev_i32_e32 v1, 31, v0
	v_lshlrev_b64 v[0:1], 2, v[0:1]
	s_lshl_b32 s0, s62, 9
	global_load_dword v20, v[4:5], off
	v_lshl_add_u64 v[4:5], s[36:37], 0, v[0:1]
	v_lshl_add_u64 v[0:1], s[38:39], 0, v[0:1]
	s_or_b32 s0, s0, s58
	global_load_dword v23, v[0:1], off
	v_or_b32_e32 v0, s0, v7
	v_ashrrev_i32_e32 v1, 31, v0
	v_readlane_b32 s0, v245, 10
	v_lshlrev_b64 v[0:1], 2, v[0:1]
	v_readlane_b32 s1, v245, 11
	global_load_dword v22, v[4:5], off
	v_lshl_add_u64 v[4:5], s[40:41], 0, v[0:1]
	v_lshl_add_u64 v[0:1], s[44:45], 0, v[0:1]
	s_load_dwordx2 s[0:1], s[0:1], 0x80
	global_load_dword v25, v[0:1], off
	v_or_b32_e32 v0, s80, v7
	v_ashrrev_i32_e32 v1, 31, v0
	v_lshlrev_b64 v[0:1], 2, v[0:1]
	global_load_dword v24, v[4:5], off
	v_lshl_add_u64 v[4:5], s[48:49], 0, v[0:1]
	global_load_dword v26, v[4:5], off
	v_lshl_add_u64 v[4:5], s[50:51], 0, v[0:1]
	s_waitcnt lgkmcnt(0)
	v_lshl_add_u64 v[0:1], s[0:1], 0, v[0:1]
	s_or_b32 s0, s62, s61
	s_ashr_i32 s1, s0, 31
	s_lshl_b64 s[0:1], s[0:1], 17
	s_add_u32 s4, s42, s0
	s_addc_u32 s5, s43, s1
	s_add_u32 s0, s46, s0
	v_lshlrev_b32_e32 v2, 2, v7
	s_addc_u32 s1, s47, s1
	global_load_dword v27, v[4:5], off
	global_load_dword v29, v[0:1], off
	s_mov_b64 s[10:11], s[4:5]
	s_mov_b64 s[12:13], s[0:1]
	v_lshlrev_b32_e32 v96, 3, v12
	v_cmp_lt_u32_e64 s[8:9], 33, v12
	v_and_b32_e32 v1, 15, v28
	v_lshrrev_b32_e32 v2, 4, v28
	v_lshl_or_b32 v4, s63, 6, v1
	v_lshlrev_b32_e32 v4, 2, v4
	v_lshl_add_u32 v4, v2, 14, v4
	v_cmp_eq_u32_e32 vcc, 1, v1
	v_lshlrev_b32_e32 v5, 4, v2
	v_lshl_add_u32 v5, v12, 9, v5
	v_cndmask_b32_e64 v1, 0, 1, vcc
	v_lshl_add_u32 v92, v1, 8, v5
	v_lshlrev_b32_e32 v93, 3, v28
	v_lshl_add_u32 v93, v12, 11, v93
	s_add_u32 s14, s10, 0x0
	s_addc_u32 s15, s11, 0
	global_load_dword v98, v4, s[14:15] offset:0
	global_load_dword v99, v4, s[14:15] offset:2048
	global_load_dword v100, v4, s[14:15] offset:64
	global_load_dword v101, v4, s[14:15] offset:2112
	global_load_dword v102, v4, s[14:15] offset:128
	global_load_dword v103, v4, s[14:15] offset:2176
	global_load_dword v104, v4, s[14:15] offset:192
	global_load_dword v105, v4, s[14:15] offset:2240
	s_add_u32 s14, s10, 0x1000
	s_addc_u32 s15, s11, 0
	global_load_dword v106, v4, s[14:15] offset:0
	global_load_dword v107, v4, s[14:15] offset:2048
	global_load_dword v108, v4, s[14:15] offset:64
	global_load_dword v109, v4, s[14:15] offset:2112
	global_load_dword v110, v4, s[14:15] offset:128
	global_load_dword v111, v4, s[14:15] offset:2176
	global_load_dword v112, v4, s[14:15] offset:192
	global_load_dword v113, v4, s[14:15] offset:2240
	s_add_u32 s14, s10, 0x2000
	s_addc_u32 s15, s11, 0
	global_load_dword v114, v4, s[14:15] offset:0
	global_load_dword v115, v4, s[14:15] offset:2048
	global_load_dword v116, v4, s[14:15] offset:64
	global_load_dword v117, v4, s[14:15] offset:2112
	global_load_dword v118, v4, s[14:15] offset:128
	global_load_dword v119, v4, s[14:15] offset:2176
	global_load_dword v120, v4, s[14:15] offset:192
	global_load_dword v121, v4, s[14:15] offset:2240
	s_add_u32 s14, s10, 0x3000
	s_addc_u32 s15, s11, 0
	global_load_dword v122, v4, s[14:15] offset:0
	global_load_dword v123, v4, s[14:15] offset:2048
	global_load_dword v124, v4, s[14:15] offset:64
	global_load_dword v125, v4, s[14:15] offset:2112
	global_load_dword v126, v4, s[14:15] offset:128
	global_load_dword v127, v4, s[14:15] offset:2176
	global_load_dword v128, v4, s[14:15] offset:192
	global_load_dword v129, v4, s[14:15] offset:2240
	s_add_u32 s14, s10, 0x10000
	s_addc_u32 s15, s11, 0
	global_load_dword v130, v4, s[14:15] offset:0
	global_load_dword v131, v4, s[14:15] offset:2048
	global_load_dword v133, v4, s[14:15] offset:64
	global_load_dword v134, v4, s[14:15] offset:2112
	global_load_dword v135, v4, s[14:15] offset:128
	global_load_dword v136, v4, s[14:15] offset:2176
	global_load_dword v137, v4, s[14:15] offset:192
	global_load_dword v138, v4, s[14:15] offset:2240
	s_add_u32 s14, s10, 0x11000
	s_addc_u32 s15, s11, 0
	global_load_dword v139, v4, s[14:15] offset:0
	global_load_dword v140, v4, s[14:15] offset:2048
	global_load_dword v141, v4, s[14:15] offset:64
	global_load_dword v142, v4, s[14:15] offset:2112
	global_load_dword v143, v4, s[14:15] offset:128
	global_load_dword v144, v4, s[14:15] offset:2176
	global_load_dword v145, v4, s[14:15] offset:192
	global_load_dword v146, v4, s[14:15] offset:2240
	s_add_u32 s14, s10, 0x12000
	s_addc_u32 s15, s11, 0
	global_load_dword v147, v4, s[14:15] offset:0
	global_load_dword v148, v4, s[14:15] offset:2048
	global_load_dword v149, v4, s[14:15] offset:64
	global_load_dword v150, v4, s[14:15] offset:2112
	global_load_dword v151, v4, s[14:15] offset:128
	global_load_dword v152, v4, s[14:15] offset:2176
	global_load_dword v153, v4, s[14:15] offset:192
	global_load_dword v154, v4, s[14:15] offset:2240
	s_add_u32 s14, s10, 0x13000
	s_addc_u32 s15, s11, 0
	global_load_dword v155, v4, s[14:15] offset:0
	global_load_dword v156, v4, s[14:15] offset:2048
	global_load_dword v157, v4, s[14:15] offset:64
	global_load_dword v158, v4, s[14:15] offset:2112
	global_load_dword v159, v4, s[14:15] offset:128
	global_load_dword v160, v4, s[14:15] offset:2176
	global_load_dword v161, v4, s[14:15] offset:192
	global_load_dword v162, v4, s[14:15] offset:2240
	s_waitcnt vmcnt(0)
; __device__ void scan_chain(PRef p, int l, int chain, ScanSm* sm) {
;     ...
;     {
;       const float* wu = p.a_w_up + ((size_t)(l * 2 + d) * 64) * 512 + hc;
;       const float* au = p.a_a_up + ((size_t)(l * 2 + d) * 64) * 512 + hc;
; #pragma unroll
;       for (int r = 0; r < 32; r++) {
;         pc.wu[r] = pack2(wu[(2 * r) * 512], wu[(2 * r + 1) * 512]);
;         pc.au[r] = pack2(au[(2 * r) * 512], au[(2 * r + 1) * 512]);
;       }
	v_cvt_pk_bf16_f32 v32, v98, v99
	v_cvt_pk_bf16_f32 v36, v100, v101
	v_cvt_pk_bf16_f32 v40, v102, v103
	v_cvt_pk_bf16_f32 v44, v104, v105
	v_cvt_pk_bf16_f32 v33, v106, v107
	v_cvt_pk_bf16_f32 v37, v108, v109
	v_cvt_pk_bf16_f32 v41, v110, v111
	v_cvt_pk_bf16_f32 v45, v112, v113
	v_cvt_pk_bf16_f32 v34, v114, v115
	v_cvt_pk_bf16_f32 v38, v116, v117
	v_cvt_pk_bf16_f32 v42, v118, v119
	v_cvt_pk_bf16_f32 v46, v120, v121
	v_cvt_pk_bf16_f32 v35, v122, v123
	v_cvt_pk_bf16_f32 v39, v124, v125
	v_cvt_pk_bf16_f32 v43, v126, v127
	v_cvt_pk_bf16_f32 v47, v128, v129
	v_cvt_pk_bf16_f32 v48, v130, v131
	v_cvt_pk_bf16_f32 v52, v133, v134
	v_cvt_pk_bf16_f32 v56, v135, v136
	v_cvt_pk_bf16_f32 v60, v137, v138
	v_cvt_pk_bf16_f32 v49, v139, v140
	v_cvt_pk_bf16_f32 v53, v141, v142
	v_cvt_pk_bf16_f32 v57, v143, v144
	v_cvt_pk_bf16_f32 v61, v145, v146
	v_cvt_pk_bf16_f32 v50, v147, v148
	v_cvt_pk_bf16_f32 v54, v149, v150
	v_cvt_pk_bf16_f32 v58, v151, v152
	v_cvt_pk_bf16_f32 v62, v153, v154
	v_cvt_pk_bf16_f32 v51, v155, v156
	v_cvt_pk_bf16_f32 v55, v157, v158
	v_cvt_pk_bf16_f32 v59, v159, v160
	v_cvt_pk_bf16_f32 v63, v161, v162
	s_add_u32 s14, s12, 0x0
	s_addc_u32 s15, s13, 0
	global_load_dword v98, v4, s[14:15] offset:0
	global_load_dword v99, v4, s[14:15] offset:2048
	global_load_dword v100, v4, s[14:15] offset:64
	global_load_dword v101, v4, s[14:15] offset:2112
	global_load_dword v102, v4, s[14:15] offset:128
	global_load_dword v103, v4, s[14:15] offset:2176
	global_load_dword v104, v4, s[14:15] offset:192
	global_load_dword v105, v4, s[14:15] offset:2240
	s_add_u32 s14, s12, 0x1000
	s_addc_u32 s15, s13, 0
	global_load_dword v106, v4, s[14:15] offset:0
	global_load_dword v107, v4, s[14:15] offset:2048
	global_load_dword v108, v4, s[14:15] offset:64
	global_load_dword v109, v4, s[14:15] offset:2112
	global_load_dword v110, v4, s[14:15] offset:128
	global_load_dword v111, v4, s[14:15] offset:2176
	global_load_dword v112, v4, s[14:15] offset:192
	global_load_dword v113, v4, s[14:15] offset:2240
	s_add_u32 s14, s12, 0x2000
	s_addc_u32 s15, s13, 0
	global_load_dword v114, v4, s[14:15] offset:0
	global_load_dword v115, v4, s[14:15] offset:2048
	global_load_dword v116, v4, s[14:15] offset:64
	global_load_dword v117, v4, s[14:15] offset:2112
	global_load_dword v118, v4, s[14:15] offset:128
	global_load_dword v119, v4, s[14:15] offset:2176
	global_load_dword v120, v4, s[14:15] offset:192
	global_load_dword v121, v4, s[14:15] offset:2240
	s_add_u32 s14, s12, 0x3000
	s_addc_u32 s15, s13, 0
	global_load_dword v122, v4, s[14:15] offset:0
	global_load_dword v123, v4, s[14:15] offset:2048
	global_load_dword v124, v4, s[14:15] offset:64
	global_load_dword v125, v4, s[14:15] offset:2112
	global_load_dword v126, v4, s[14:15] offset:128
	global_load_dword v127, v4, s[14:15] offset:2176
	global_load_dword v128, v4, s[14:15] offset:192
	global_load_dword v129, v4, s[14:15] offset:2240
	s_add_u32 s14, s12, 0x10000
	s_addc_u32 s15, s13, 0
	global_load_dword v130, v4, s[14:15] offset:0
	global_load_dword v131, v4, s[14:15] offset:2048
	global_load_dword v133, v4, s[14:15] offset:64
	global_load_dword v134, v4, s[14:15] offset:2112
	global_load_dword v135, v4, s[14:15] offset:128
	global_load_dword v136, v4, s[14:15] offset:2176
	global_load_dword v137, v4, s[14:15] offset:192
	global_load_dword v138, v4, s[14:15] offset:2240
	s_add_u32 s14, s12, 0x11000
	s_addc_u32 s15, s13, 0
	global_load_dword v139, v4, s[14:15] offset:0
	global_load_dword v140, v4, s[14:15] offset:2048
	global_load_dword v141, v4, s[14:15] offset:64
	global_load_dword v142, v4, s[14:15] offset:2112
	global_load_dword v143, v4, s[14:15] offset:128
	global_load_dword v144, v4, s[14:15] offset:2176
	global_load_dword v145, v4, s[14:15] offset:192
	global_load_dword v146, v4, s[14:15] offset:2240
	s_add_u32 s14, s12, 0x12000
	s_addc_u32 s15, s13, 0
	global_load_dword v147, v4, s[14:15] offset:0
	global_load_dword v148, v4, s[14:15] offset:2048
	global_load_dword v149, v4, s[14:15] offset:64
	global_load_dword v150, v4, s[14:15] offset:2112
	global_load_dword v151, v4, s[14:15] offset:128
	global_load_dword v152, v4, s[14:15] offset:2176
	global_load_dword v153, v4, s[14:15] offset:192
	global_load_dword v154, v4, s[14:15] offset:2240
	s_add_u32 s14, s12, 0x13000
	s_addc_u32 s15, s13, 0
	global_load_dword v155, v4, s[14:15] offset:0
	global_load_dword v156, v4, s[14:15] offset:2048
	global_load_dword v157, v4, s[14:15] offset:64
	global_load_dword v158, v4, s[14:15] offset:2112
	global_load_dword v159, v4, s[14:15] offset:128
	global_load_dword v160, v4, s[14:15] offset:2176
	global_load_dword v161, v4, s[14:15] offset:192
	global_load_dword v162, v4, s[14:15] offset:2240
	s_waitcnt vmcnt(0)
	v_cvt_pk_bf16_f32 v64, v98, v99
	v_cvt_pk_bf16_f32 v68, v100, v101
	v_cvt_pk_bf16_f32 v72, v102, v103
	v_cvt_pk_bf16_f32 v76, v104, v105
	v_cvt_pk_bf16_f32 v65, v106, v107
	v_cvt_pk_bf16_f32 v69, v108, v109
	v_cvt_pk_bf16_f32 v73, v110, v111
	v_cvt_pk_bf16_f32 v77, v112, v113
	v_cvt_pk_bf16_f32 v66, v114, v115
	v_cvt_pk_bf16_f32 v70, v116, v117
	v_cvt_pk_bf16_f32 v74, v118, v119
	v_cvt_pk_bf16_f32 v78, v120, v121
	v_cvt_pk_bf16_f32 v67, v122, v123
	v_cvt_pk_bf16_f32 v71, v124, v125
	v_cvt_pk_bf16_f32 v75, v126, v127
	v_cvt_pk_bf16_f32 v79, v128, v129
	v_cvt_pk_bf16_f32 v80, v130, v131
	v_cvt_pk_bf16_f32 v84, v133, v134
	v_cvt_pk_bf16_f32 v88, v135, v136
	v_cvt_pk_bf16_f32 v210, v137, v138
	v_cvt_pk_bf16_f32 v81, v139, v140
	v_cvt_pk_bf16_f32 v85, v141, v142
	v_cvt_pk_bf16_f32 v89, v143, v144
	v_cvt_pk_bf16_f32 v211, v145, v146
	v_cvt_pk_bf16_f32 v82, v147, v148
	v_cvt_pk_bf16_f32 v86, v149, v150
	v_cvt_pk_bf16_f32 v90, v151, v152
	v_cvt_pk_bf16_f32 v212, v153, v154
	v_cvt_pk_bf16_f32 v83, v155, v156
	v_cvt_pk_bf16_f32 v87, v157, v158
	v_cvt_pk_bf16_f32 v91, v159, v160
	v_cvt_pk_bf16_f32 v213, v161, v162
	s_cmp_eq_u32 s62, 0
	s_cselect_b64 s[4:5], -1, 0
	s_cmp_lg_u32 s62, 0
	s_cselect_b64 s[0:1], -1, 0
	v_cndmask_b32_e64 v0, 0, 1, s[0:1]
	v_cmp_ne_u32_e64 s[6:7], 1, v0
	s_and_saveexec_b64 s[0:1], s[8:9]
	s_xor_b64 s[10:11], exec, s[0:1]
	s_cbranch_execz .LBB0_573
	s_and_b64 vcc, exec, s[6:7]
	s_mov_b64 s[12:13], -1
	s_cbranch_vccnz .LBB0_571
	v_sub_u32_e32 v0, 0x90f, v96
	s_mov_b64 s[12:13], 0

; DEV void prep_load(PRef p, const PrepConst& pc, int b, int d, int s, PrepRaw& rw) {
;   bool isctx = s < 256;
;   int pos = isctx ? (d ? 255 - s : s) : (d ? 2047 - (s - 256) : s - 256);
;   int seglen = isctx ? 256 : 2048;
;   int row = b * TPB + (isctx ? 0 : 256) + pos;
;   rw.row = row;
;   bool hp = pos > 0, hn = pos < seglen - 1;
;   const bf16* z = p.ZA + (size_t)row * 1792;
;   const bf16* zpp = hp ? z - 1792 : z;
;   const bf16* znp = hn ? z + 1792 : z;
;   rw.fp = hp ? 1.f : 0.f;
;   rw.fn = hn ? 1.f : 0.f;
; #pragma unroll
;   for (int i = 0; i < 5; i++) {
;     int col = pc.cols[i];
;     rw.zc[i] = z[col];
;     rw.zp[i] = zpp[col];
;     rw.zn[i] = znp[col];
;   }
; }
; __device__ void scan_chain(PRef p, int l, int chain, ScanSm* sm) {
;     ...
;     float* stw = &sm->st[wave][0][0];
;     const int base = (wave - 2) * 8;
;     int i = base, c = 0;
;     float Dprev = 1.f;
;     PrepRaw rwA, rwB, rnA, rnB;
;     prep_load(p, pc, b, d, i, rwA);
;     prep_load(p, pc, b, d, i + 1, rwB);
.LBB0_580:
	s_or_saveexec_b64 s[8:9], s[8:9]
	v_mov_b32_e32 v2, 0x7ff
	v_mov_b32_e32 v9, 0x100
	s_xor_b64 exec, exec, s[8:9]
	v_add_u32_e32 v1, -15, v96
	v_sub_u32_e32 v2, 0x10e, v96
	v_cndmask_b32_e64 v1, v2, v1, s[4:5]
	v_mov_b32_e32 v2, 0xff
	v_mov_b32_e32 v9, 0
	s_or_b64 exec, exec, s[8:9]
	v_lshlrev_b32_e32 v95, 9, v12
	v_add3_u32 v12, v9, s28, v1
	v_cmp_lt_i32_e32 vcc, 0, v1
	v_cmp_lt_i32_e64 s[8:9], v1, v2
	v_mov_b64_e32 v[98:99], s[70:71]
	v_mad_i64_i32 v[98:99], s[0:1], v12, s94, v[98:99]
	v_cndmask_b32_e64 v101, 0, -1, vcc
	v_cndmask_b32_e32 v100, 0, v203, vcc
	v_cndmask_b32_e64 v2, 0, v204, s[8:9]
	v_lshl_add_u64 v[100:101], v[98:99], 0, v[100:101]
	v_lshl_add_u64 v[102:103], v[98:99], 0, v[2:3]
	v_mov_b32_e32 v1, v3
	v_lshl_add_u64 v[104:105], v[98:99], 0, v[0:1]
	v_lshl_add_u64 v[106:107], v[100:101], 0, v[0:1]
	v_lshl_add_u64 v[108:109], v[102:103], 0, v[0:1]
	global_load_ushort v160, v[104:105], off
	global_load_ushort v163, v[106:107], off
	global_load_ushort v164, v[108:109], off
	global_load_ushort v158, v[104:105], off offset:1024
	global_load_ushort v161, v[106:107], off offset:1024
	global_load_ushort v162, v[108:109], off offset:1024
	global_load_ushort v153, v[104:105], off offset:2048
	global_load_ushort v155, v[106:107], off offset:2048
	global_load_ushort v157, v[108:109], off offset:2048
	v_mov_b32_e32 v9, v3
	v_lshl_add_u64 v[98:99], v[98:99], 0, v[8:9]
	v_lshl_add_u64 v[100:101], v[100:101], 0, v[8:9]
	v_lshl_add_u64 v[102:103], v[102:103], 0, v[8:9]
	global_load_ushort v151, v[98:99], off offset:3072
	global_load_ushort v154, v[100:101], off offset:3072
	global_load_ushort v159, v[102:103], off offset:3072
	global_load_ushort v150, v[98:99], off offset:3328
	global_load_ushort v152, v[100:101], off offset:3328
	global_load_ushort v156, v[102:103], off offset:3328
	s_lshl_b32 s0, s62, 5
	s_add_u32 s0, s18, s0
	v_cndmask_b32_e64 v146, 0, 1.0, s[10:11]
	s_addc_u32 s1, s19, 0
	s_lshl_b32 s10, s63, 2
	s_add_u32 s22, s0, s10
	v_mov_b32_e32 v4, 1.0
	v_cndmask_b32_e64 v147, 0, 1.0, s[12:13]
	v_cndmask_b32_e64 v148, 0, 1.0, vcc
	v_cndmask_b32_e64 v149, 0, 1.0, s[8:9]
	v_add_u32_e32 v96, -8, v96
	v_lshl_or_b32 v97, v28, 1, v95
	v_cmp_eq_u32_e64 s[8:9], 0, v28
	s_addc_u32 s23, s1, 0
	v_mov_b32_e32 v145, 0
	s_mov_b64 s[26:27], 0
	v_mov_b32_e32 v165, v30
	s_branch .LBB0_584

; DEV float bf2f(bf16 h) { return __uint_as_float(((uint32_t)h) << 16); }
; DEV void wbar() { __builtin_amdgcn_wave_barrier(); }
; DEV void prep_compute2(PRef p, const PrepConst& pc, const PrepRaw& rwA, const PrepRaw& rwB, int h, int d,
;                        ScanRec* rcA, ScanRec* rcB, float* stw, int lane, float& Dprev) {
;   float valsA[5], valsB[5];
; #pragma unroll
;   for (int i = 0; i < 5; i++) {
;     float zc = bf2f(rwA.zc[i]), zp = rwA.fp * bf2f(rwA.zp[i]), zn = rwA.fn * bf2f(rwA.zn[i]);
;     valsA[i] = zc + pc.mup[i] * (zp - zc) + pc.mun[i] * (zn - zc);
;     float zc2 = bf2f(rwB.zc[i]), zp2 = rwB.fp * bf2f(rwB.zp[i]), zn2 = rwB.fn * bf2f(rwB.zn[i]);
;     valsB[i] = zc2 + pc.mup[i] * (zp2 - zc2) + pc.mun[i] * (zn2 - zc2);
;   }
;   float thA = 1.f - __fdividef(2.f, 1.f + __expf(2.f * valsA[3]));
;   float thB = 1.f - __fdividef(2.f, 1.f + __expf(2.f * valsB[3]));
;   bf16* stb = (bf16*)stw;
;   wbar();
;   stb[lane] = f2bf(thA);
;   stb[64 + lane] = f2bf(valsA[4]);
;   stb[128 + lane] = f2bf(thB);
;   stb[192 + lane] = f2bf(valsB[4]);
;   wbar();
;   float wA0 = pc.w0v, wA1 = 0.f, aA0 = pc.a0v, aA1 = 0.f;
;   float wB0 = pc.w0v, wB1 = 0.f, aB0 = pc.a0v, aB1 = 0.f;
;   const uint4* st4 = (const uint4*)stw;
; #pragma unroll
;   for (int g = 0; g < 8; g++) {
;     uint4 tA = st4[g], uA = st4[8 + g], tB = st4[16 + g], uB = st4[24 + g];
;     uint32_t w0 = pc.wu[4 * g], w1 = pc.wu[4 * g + 1], w2 = pc.wu[4 * g + 2], w3 = pc.wu[4 * g + 3];
;     uint32_t u0 = pc.au[4 * g], u1 = pc.au[4 * g + 1], u2 = pc.au[4 * g + 2], u3 = pc.au[4 * g + 3];
;     wA0 = dot2bf(tA.x, w0, wA0); wB0 = dot2bf(tB.x, w0, wB0);
;     wA1 = dot2bf(tA.y, w1, wA1); wB1 = dot2bf(tB.y, w1, wB1);
;     wA0 = dot2bf(tA.z, w2, wA0); wB0 = dot2bf(tB.z, w2, wB0);
;     wA1 = dot2bf(tA.w, w3, wA1); wB1 = dot2bf(tB.w, w3, wB1);
;     aA0 = dot2bf(uA.x, u0, aA0); aB0 = dot2bf(uB.x, u0, aB0);
;     aA1 = dot2bf(uA.y, u1, aA1); aB1 = dot2bf(uB.y, u1, aB1);
;     aA0 = dot2bf(uA.z, u2, aA0); aB0 = dot2bf(uB.z, u2, aB0);
;     aA1 = dot2bf(uA.w, u3, aA1); aB1 = dot2bf(uB.w, u3, aB1);
;   }
.LBB0_601:
	s_or_b64 exec, exec, s[30:31]
	v_cmp_ne_u32_e32 vcc, v165, v30
	s_waitcnt vmcnt(29)
	v_lshlrev_b32_e32 v141, 16, v141
	s_waitcnt vmcnt(26)
	v_lshlrev_b32_e32 v137, 16, v137
	v_cndmask_b32_e32 v143, 1.0, v4, vcc
	v_and_b32_e32 v4, 1, v145
	v_mul_lo_u32 v145, v165, s65
	v_mad_u32_u24 v145, v4, s97, v145
	v_lshlrev_b32_e32 v4, 16, v142
	v_lshlrev_b32_e32 v142, 16, v144
	v_fma_f32 v4, v146, v4, -v141
	v_fma_f32 v142, v147, v142, -v141
	v_fmac_f32_e32 v141, v14, v4
	v_fmac_f32_e32 v141, v16, v142
	s_waitcnt vmcnt(14)
	v_lshlrev_b32_e32 v142, 16, v160
	s_waitcnt vmcnt(13)
	v_lshlrev_b32_e32 v4, 16, v163
	s_waitcnt vmcnt(12)
	v_lshlrev_b32_e32 v144, 16, v164
	v_fma_f32 v4, v148, v4, -v142
	v_fma_f32 v144, v149, v144, -v142
	v_fmac_f32_e32 v142, v14, v4
	v_lshlrev_b32_e32 v4, 16, v138
	v_lshlrev_b32_e32 v138, 16, v140
	v_fma_f32 v4, v146, v4, -v137
	v_fma_f32 v138, v147, v138, -v137
	v_fmac_f32_e32 v137, v15, v4
	v_fmac_f32_e32 v137, v17, v138
	s_waitcnt vmcnt(11)
	v_lshlrev_b32_e32 v138, 16, v158
	s_waitcnt vmcnt(10)
	v_lshlrev_b32_e32 v4, 16, v161
	s_waitcnt vmcnt(9)
	v_lshlrev_b32_e32 v140, 16, v162
	v_fma_f32 v4, v148, v4, -v138
	v_fma_f32 v140, v149, v140, -v138
	v_fmac_f32_e32 v138, v15, v4
	v_lshlrev_b32_e32 v134, 16, v134
	v_lshlrev_b32_e32 v4, 16, v135
	v_lshlrev_b32_e32 v135, 16, v139
	v_fma_f32 v4, v146, v4, -v134
	v_fma_f32 v135, v147, v135, -v134
	v_fmac_f32_e32 v134, v18, v4
	v_fmac_f32_e32 v134, v19, v135
	s_waitcnt vmcnt(8)
	v_lshlrev_b32_e32 v135, 16, v153
	s_waitcnt vmcnt(7)
	v_lshlrev_b32_e32 v4, 16, v155
	s_waitcnt vmcnt(6)
	v_lshlrev_b32_e32 v139, 16, v157
	v_fma_f32 v4, v148, v4, -v135
	v_fma_f32 v139, v149, v139, -v135
	v_fmac_f32_e32 v135, v18, v4
	v_lshlrev_b32_e32 v4, 16, v11
	v_lshlrev_b32_e32 v11, 16, v13
	v_lshlrev_b32_e32 v13, 16, v136
	v_fma_f32 v11, v146, v11, -v4
	v_fma_f32 v13, v147, v13, -v4
	v_fmac_f32_e32 v4, v20, v11
	v_fmac_f32_e32 v4, v21, v13
	v_add_f32_e32 v4, v4, v4
	v_mul_f32_e32 v4, 0x3fb8aa3b, v4
	v_lshlrev_b32_e32 v5, 16, v5
	v_lshlrev_b32_e32 v6, 16, v6
	v_exp_f32_e32 v4, v4
	v_lshlrev_b32_e32 v7, 16, v7
	v_fma_f32 v6, v146, v6, -v5
	s_waitcnt vmcnt(5)
	v_lshlrev_b32_e32 v11, 16, v151
	s_waitcnt vmcnt(4)
	v_lshlrev_b32_e32 v13, 16, v154
	v_fma_f32 v7, v147, v7, -v5
	v_fmac_f32_e32 v5, v22, v6
	s_waitcnt vmcnt(3)
	v_lshlrev_b32_e32 v136, 16, v159
	v_fma_f32 v13, v148, v13, -v11
	v_fmac_f32_e32 v5, v23, v7
	s_waitcnt vmcnt(2)
	v_lshlrev_b32_e32 v6, 16, v150
	s_waitcnt vmcnt(1)
	v_lshlrev_b32_e32 v7, 16, v152
	s_and_b64 s[0:1], exec, s[12:13]
	v_fma_f32 v136, v149, v136, -v11
	v_fmac_f32_e32 v11, v20, v13
	s_waitcnt vmcnt(0)
	v_lshlrev_b32_e32 v13, 16, v156
	v_fma_f32 v7, v148, v7, -v6
	v_add_f32_e32 v4, 1.0, v4
	s_or_b64 s[26:27], s[0:1], s[26:27]
	v_fma_f32 v13, v149, v13, -v6
	v_fmac_f32_e32 v6, v22, v7
	v_fmac_f32_e32 v6, v23, v13
	v_fmac_f32_e32 v11, v21, v136
	v_fmac_f32_e32 v135, v19, v139
	v_fmac_f32_e32 v138, v17, v140
	v_rcp_f32_e32 v4, v4
	v_add_f32_e32 v7, v11, v11
	v_mul_f32_e32 v7, 0x3fb8aa3b, v7
	v_exp_f32_e32 v7, v7
	v_fma_f32 v4, v4, -2.0, 1.0
	v_fmac_f32_e32 v142, v16, v144
	v_add_f32_e32 v7, 1.0, v7
	v_cvt_pk_bf16_f32 v4, v4, s0
	ds_write_b16 v97, v4 offset:49152
	v_cvt_pk_bf16_f32 v4, v5, s0
	v_rcp_f32_e32 v7, v7
	s_nop 0
	v_fma_f32 v7, v7, -2.0, 1.0
	ds_write_b16 v97, v4 offset:49280
	v_cvt_pk_bf16_f32 v4, v7, s0
	ds_write_b16 v97, v4 offset:49408
	v_cvt_pk_bf16_f32 v4, v6, s0
	ds_write_b16 v97, v4 offset:49536
	ds_read_b128 v[146:149], v92 offset:49152
	ds_read_b128 v[150:153], v92 offset:49216
	ds_read_b128 v[154:157], v92 offset:49280
	ds_read_b128 v[158:161], v92 offset:49344
	s_waitcnt lgkmcnt(3)
	v_mfma_f32_16x16x32_bf16 v[162:165], v[146:149], v[32:35], 0
	v_mfma_f32_16x16x32_bf16 v[166:169], v[146:149], v[36:39], 0
	v_mfma_f32_16x16x32_bf16 v[170:173], v[146:149], v[40:43], 0
	v_mfma_f32_16x16x32_bf16 v[174:177], v[146:149], v[44:47], 0
	s_waitcnt lgkmcnt(2)
	v_mfma_f32_16x16x32_bf16 v[162:165], v[150:153], v[48:51], v[162:165]
	v_mfma_f32_16x16x32_bf16 v[166:169], v[150:153], v[52:55], v[166:169]
	v_mfma_f32_16x16x32_bf16 v[170:173], v[150:153], v[56:59], v[170:173]
	v_mfma_f32_16x16x32_bf16 v[174:177], v[150:153], v[60:63], v[174:177]
	s_waitcnt lgkmcnt(1)
	v_mfma_f32_16x16x32_bf16 v[214:217], v[154:157], v[64:67], 0
	v_mfma_f32_16x16x32_bf16 v[218:221], v[154:157], v[68:71], 0
	v_mfma_f32_16x16x32_bf16 v[222:225], v[154:157], v[72:75], 0
	v_mfma_f32_16x16x32_bf16 v[226:229], v[154:157], v[76:79], 0
	s_waitcnt lgkmcnt(0)
	v_mfma_f32_16x16x32_bf16 v[214:217], v[158:161], v[80:83], v[214:217]
	v_mfma_f32_16x16x32_bf16 v[218:221], v[158:161], v[84:87], v[218:221]
	v_mfma_f32_16x16x32_bf16 v[222:225], v[158:161], v[88:91], v[222:225]
	v_mfma_f32_16x16x32_bf16 v[226:229], v[158:161], v[210:213], v[226:229]
	s_nop 1
	s_mov_b64 exec, 0xffff
	ds_write_b64 v93, v[162:163] offset:51232
	ds_write_b64 v93, v[166:167] offset:51360
	ds_write_b64 v93, v[170:171] offset:51488
	ds_write_b64 v93, v[174:175] offset:51616
	s_nop 1
	ds_write_b64 v93, v[214:215] offset:51744
	ds_write_b64 v93, v[218:219] offset:51872
	ds_write_b64 v93, v[222:223] offset:52000
	ds_write_b64 v93, v[226:227] offset:52128
	s_mov_b64 exec, -1
	ds_read_b64 v[148:149], v93 offset:51232
	ds_read_b64 v[146:147], v93 offset:51744
	s_waitcnt lgkmcnt(1)
	v_add_f32_e32 v4, v24, v148
	v_add_f32_e32 v5, v24, v149
	s_waitcnt lgkmcnt(0)
; DEV void prep_compute2(PRef p, const PrepConst& pc, const PrepRaw& rwA, const PrepRaw& rwB, int h, int d,
;                        ScanRec* rcA, ScanRec* rcB, float* stw, int lane, float& Dprev) {
;     ...
;   float zzA = -(wA0 + wA1), zzB = -(wB0 + wB1);
;   float spA = zzA > 20.f ? zzA : __logf(1.f + __expf(zzA));
;   float spB = zzB > 20.f ? zzB : __logf(1.f + __expf(zzB));
;   float decA = __expf(-__expf(-spA - 0.5f)), decB = __expf(-__expf(-spB - 0.5f));
;   float aA = __fdividef(1.f, 1.f + __expf(-(aA0 + aA1))), aB = __fdividef(1.f, 1.f + __expf(-(aB0 + aB1)));
;   float kkA = valsA[1] * pc.kkc, kkB = valsB[1] * pc.kkc;
;   float ssA = wave_sum(kkA * kkA), ssB = wave_sum(kkB * kkB);
;   kkA *= rsqrtf(fmaxf(ssA, 1e-24f));
;   kkB *= rsqrtf(fmaxf(ssB, 1e-24f));
;   float kdA = valsA[1] * (1.f + (aA - 1.f) * pc.kac), kdB = valsB[1] * (1.f + (aB - 1.f) * pc.kac);
;   float bonA = wave_sum(valsA[0] * kdA * pc.rkc), bonB = wave_sum(valsB[0] * kdB * pc.rkc);
;   float DA = Dprev * decA, DB = DA * decB;
;   float iDA = __fdividef(1.f, DA), iDB = __fdividef(1.f, DB);
;   rcA->w[lane] = DA; rcB->w[lane] = DB;
;   rcA->kk[lane] = kkA * Dprev; rcB->kk[lane] = kkB * DA;
;   rcA->kka[lane] = kkA * aA * iDA; rcB->kka[lane] = kkB * aB * iDB;
;   rcA->kd[lane] = kdA * iDA; rcB->kd[lane] = kdB * iDB;
;   rcA->r[lane] = valsA[0] * DA; rcB->r[lane] = valsB[0] * DB;
;   rcA->v[lane] = valsA[2]; rcB->v[lane] = valsB[2];
;   Dprev = DB;
;   if (lane == 0) {
;     p.SB[(size_t)rwA.row * 16 + d * 8 + h] = bonA;
;     p.SB[(size_t)rwB.row * 16 + d * 8 + h] = bonB;
;   }
	v_add_f32_e32 v136, v25, v146
	v_add_f32_e32 v11, v25, v147
	s_mov_b32 s1, 0x3f317217
	s_mov_b32 s16, 0x7f800000
	s_mov_b32 s0, 0xc1a00000
	v_mul_f32_e32 v6, 0xbfb8aa3b, v4
	v_exp_f32_e32 v6, v6
	v_cmp_gt_f32_e32 vcc, s0, v4
	v_add_f32_e32 v6, 1.0, v6
	v_cmp_gt_f32_e64 s[12:13], s2, v6
	s_nop 1
	v_cndmask_b32_e64 v7, 0, 32, s[12:13]
	v_ldexp_f32 v6, v6, v7
	v_log_f32_e32 v6, v6
	s_nop 0
	v_mul_f32_e32 v7, 0x3f317217, v6
	v_fma_f32 v7, v6, s1, -v7
	v_fmac_f32_e32 v7, 0x3377d1cf, v6
	v_fmac_f32_e32 v7, 0x3f317217, v6
	v_cmp_lt_f32_e64 s[14:15], |v6|, s16
	s_nop 1
	v_cndmask_b32_e64 v6, v6, v7, s[14:15]
	v_cndmask_b32_e64 v7, 0, v205, s[12:13]
	v_sub_f32_e32 v6, v6, v7
	v_cndmask_b32_e64 v4, v6, -v4, vcc
	v_mul_f32_e32 v6, 0xbfb8aa3b, v5
	v_exp_f32_e32 v6, v6
	v_cmp_gt_f32_e32 vcc, s0, v5
	v_sub_f32_e32 v4, -0.5, v4
	v_add_f32_e32 v6, 1.0, v6
	v_cmp_gt_f32_e64 s[12:13], s2, v6
	v_mul_f32_e32 v4, 0x3fb8aa3b, v4
	v_exp_f32_e32 v4, v4
	v_cndmask_b32_e64 v7, 0, 32, s[12:13]
	v_ldexp_f32 v6, v6, v7
	v_log_f32_e32 v6, v6
	v_mul_f32_e32 v4, 0xbfb8aa3b, v4
	v_exp_f32_e32 v4, v4
	v_mul_f32_e32 v7, 0x3f317217, v6
	v_fma_f32 v7, v6, s1, -v7
	v_fmac_f32_e32 v7, 0x3377d1cf, v6
	v_fmac_f32_e32 v7, 0x3f317217, v6
	v_cmp_lt_f32_e64 s[14:15], |v6|, s16
	s_nop 1
	v_cndmask_b32_e64 v6, v6, v7, s[14:15]
	v_cndmask_b32_e64 v7, 0, v205, s[12:13]
	v_sub_f32_e32 v6, v6, v7
	v_cndmask_b32_e64 v5, v6, -v5, vcc
	v_mul_f32_e32 v6, 0xbfb8aa3b, v136
	v_exp_f32_e32 v6, v6
	v_sub_f32_e32 v5, -0.5, v5
	v_mul_f32_e32 v5, 0x3fb8aa3b, v5
	v_exp_f32_e32 v5, v5
	v_add_f32_e32 v6, 1.0, v6
	v_mul_f32_e32 v5, 0xbfb8aa3b, v5
	v_exp_f32_e32 v5, v5
	v_rcp_f32_e32 v6, v6
	v_mul_f32_e32 v7, 0xbfb8aa3b, v11
	v_exp_f32_e32 v7, v7
	s_nop 0
	v_add_f32_e32 v7, 1.0, v7
	v_rcp_f32_e32 v7, v7
	v_mul_f32_e32 v11, v26, v137
	v_mul_f32_e32 v136, v11, v11
	v_mul_f32_e32 v13, v26, v138
	s_nop 0
	v_mov_b32_dpp v136, v136 quad_perm:[1,0,3,2] row_mask:0xf bank_mask:0xf bound_ctrl:1
	v_fmac_f32_e32 v136, v11, v11
	s_nop 1
	v_add_f32_dpp v136, v136, v136 quad_perm:[2,3,0,1] row_mask:0xf bank_mask:0xf bound_ctrl:1
	s_nop 1
	v_add_f32_dpp v136, v136, v136 row_half_mirror row_mask:0xf bank_mask:0xf bound_ctrl:1
	s_nop 1
	v_add_f32_dpp v136, v136, v136 row_mirror row_mask:0xf bank_mask:0xf bound_ctrl:1
	s_nop 0
	v_readlane_b32 s1, v136, 16
	v_readlane_b32 s13, v136, 48
	v_readlane_b32 s0, v136, 0
	v_readlane_b32 s12, v136, 32
	v_mov_b32_e32 v136, s1
	v_mov_b32_e32 v139, s13
	v_add_f32_e32 v136, s0, v136
	v_add_f32_e32 v139, s12, v139
	v_add_f32_e32 v136, v136, v139
	v_mul_f32_e32 v139, v13, v13
	v_max_f32_e32 v136, 0x179abe15, v136
	v_rsq_f32_e32 v136, v136
	v_mov_b32_dpp v139, v139 quad_perm:[1,0,3,2] row_mask:0xf bank_mask:0xf bound_ctrl:1
	v_fmac_f32_e32 v139, v13, v13
	v_mul_f32_e32 v11, v11, v136
	s_nop 0
	v_add_f32_dpp v139, v139, v139 quad_perm:[2,3,0,1] row_mask:0xf bank_mask:0xf bound_ctrl:1
	s_nop 1
	v_add_f32_dpp v139, v139, v139 row_half_mirror row_mask:0xf bank_mask:0xf bound_ctrl:1
	s_nop 1
	v_add_f32_dpp v139, v139, v139 row_mirror row_mask:0xf bank_mask:0xf bound_ctrl:1
	s_nop 0
	v_readlane_b32 s1, v139, 16
	v_readlane_b32 s13, v139, 48
	v_readlane_b32 s0, v139, 0
	v_readlane_b32 s12, v139, 32
	v_mov_b32_e32 v139, s1
	v_mov_b32_e32 v140, s13
	v_add_f32_e32 v139, s0, v139
	v_add_f32_e32 v140, s12, v140
	v_add_f32_e32 v139, v139, v140
	v_max_f32_e32 v136, 0x179abe15, v139
	v_rsq_f32_e32 v136, v136
	s_nop 0
	v_mul_f32_e32 v13, v13, v136
	v_add_f32_e32 v136, -1.0, v6
	v_fma_f32 v136, v27, v136, 1.0
	v_mul_f32_e32 v136, v137, v136
	v_add_f32_e32 v137, -1.0, v7
	v_fma_f32 v137, v27, v137, 1.0
	v_mul_f32_e32 v137, v138, v137
	v_mul_f32_e32 v138, v141, v136
	v_mul_f32_e32 v139, v29, v138
	v_mul_f32_e32 v6, v6, v11
	v_mul_f32_e32 v7, v7, v13
	v_mov_b32_dpp v139, v139 quad_perm:[1,0,3,2] row_mask:0xf bank_mask:0xf bound_ctrl:1
	v_fmac_f32_e32 v139, v29, v138
	s_nop 1
	v_add_f32_dpp v138, v139, v139 quad_perm:[2,3,0,1] row_mask:0xf bank_mask:0xf bound_ctrl:1
	s_nop 1
	v_add_f32_dpp v138, v138, v138 row_half_mirror row_mask:0xf bank_mask:0xf bound_ctrl:1
	s_nop 1
	v_add_f32_dpp v138, v138, v138 row_mirror row_mask:0xf bank_mask:0xf bound_ctrl:1
	s_nop 0
	v_readlane_b32 s0, v138, 0
	v_readlane_b32 s14, v138, 16
	v_readlane_b32 s1, v138, 32
	v_readlane_b32 s15, v138, 48
	v_mul_f32_e32 v138, v142, v137
	v_mul_f32_e32 v139, v29, v138
	s_nop 1
	v_mov_b32_dpp v139, v139 quad_perm:[1,0,3,2] row_mask:0xf bank_mask:0xf bound_ctrl:1
	v_fmac_f32_e32 v139, v29, v138
	s_nop 1
	v_add_f32_dpp v138, v139, v139 quad_perm:[2,3,0,1] row_mask:0xf bank_mask:0xf bound_ctrl:1
	s_nop 1
	v_add_f32_dpp v138, v138, v138 row_half_mirror row_mask:0xf bank_mask:0xf bound_ctrl:1
	s_nop 1
	v_add_f32_dpp v138, v138, v138 row_mirror row_mask:0xf bank_mask:0xf bound_ctrl:1
	s_nop 0
	v_readlane_b32 s16, v138, 0
	v_readlane_b32 s30, v138, 16
	v_readlane_b32 s17, v138, 32
	v_readlane_b32 s31, v138, 48
	v_mul_f32_e32 v138, v143, v4
	v_mul_f32_e32 v4, v138, v5
	v_mul_f32_e32 v143, v143, v11
	v_rcp_f32_e32 v5, v138
	v_rcp_f32_e32 v139, v4
	v_mul_f32_e32 v6, v5, v6
	v_mul_f32_e32 v5, v5, v136
	v_lshl_or_b32 v140, v28, 2, v145
	v_mul_f32_e32 v7, v139, v7
	ds_write2st64_b32 v140, v6, v5 offset0:2 offset1:3
	v_mul_f32_e32 v5, v139, v137
	ds_write2st64_b32 v140, v138, v143 offset1:1
	v_mul_f32_e32 v143, v138, v13
	ds_write2st64_b32 v140, v7, v5 offset0:8 offset1:9
	v_mul_f32_e32 v5, v141, v138
	ds_write2st64_b32 v140, v4, v143 offset0:6 offset1:7
	v_mul_f32_e32 v6, v142, v4
	ds_write2st64_b32 v140, v5, v134 offset0:4 offset1:5
	ds_write2st64_b32 v140, v6, v135 offset0:10 offset1:11
	s_and_saveexec_b64 s[12:13], s[8:9]
	s_cbranch_execz .LBB0_603
	v_mov_b32_e32 v5, s30
	v_mov_b32_e32 v6, s31
	v_add_f32_e32 v5, s16, v5
	v_add_f32_e32 v6, s17, v6
	v_add_f32_e32 v5, v5, v6
	v_mov_b32_e32 v6, s14
	v_mov_b32_e32 v7, s15
	v_add_f32_e32 v6, s0, v6
	v_add_f32_e32 v7, s1, v7
	v_ashrrev_i32_e32 v11, 31, v10
	v_add_f32_e32 v13, v6, v7
	v_lshlrev_b64 v[6:7], 6, v[10:11]
	v_lshl_add_u64 v[6:7], s[22:23], 0, v[6:7]
	global_store_dword v[6:7], v13, off
	v_ashrrev_i32_e32 v13, 31, v12
	v_lshlrev_b64 v[6:7], 6, v[12:13]
	v_lshl_add_u64 v[6:7], s[22:23], 0, v[6:7]
	global_store_dword v[6:7], v5, off

; __global__ void __launch_bounds__(256, 2) fwd_megakernel(Params p) {
;   cg::grid_group grid = cg::this_grid();
;   __shared__ __attribute__((aligned(16))) unsigned char smem[SMEM_BYTES];
	.amdhsa_kernel _Z14fwd_megakernel6Params
		.amdhsa_group_segment_fixed_size 58400
		.amdhsa_private_segment_fixed_size 0
		.amdhsa_kernarg_size 664
		.amdhsa_user_sgpr_count 2
		.amdhsa_user_sgpr_dispatch_ptr 0
		.amdhsa_user_sgpr_queue_ptr 0
		.amdhsa_user_sgpr_kernarg_segment_ptr 1
		.amdhsa_user_sgpr_dispatch_id 0
		.amdhsa_user_sgpr_kernarg_preload_length 0
		.amdhsa_user_sgpr_kernarg_preload_offset 0
		.amdhsa_user_sgpr_private_segment_size 0
		.amdhsa_uses_dynamic_stack 0
		.amdhsa_enable_private_segment 0
		.amdhsa_system_sgpr_workgroup_id_x 1
		.amdhsa_system_sgpr_workgroup_id_y 0
		.amdhsa_system_sgpr_workgroup_id_z 0
		.amdhsa_system_sgpr_workgroup_info 0
		.amdhsa_system_vgpr_workitem_id 2
		.amdhsa_next_free_vgpr 247
		.amdhsa_next_free_sgpr 98
		.amdhsa_accum_offset 248
		.amdhsa_reserve_vcc 1
		.amdhsa_float_round_mode_32 0
		.amdhsa_float_round_mode_16_64 0
		.amdhsa_float_denorm_mode_32 3
		.amdhsa_float_denorm_mode_16_64 3
		.amdhsa_dx10_clamp 1
		.amdhsa_ieee_mode 1
		.amdhsa_fp16_overflow 0
		.amdhsa_tg_split 0
		.amdhsa_exception_fp_ieee_invalid_op 0
		.amdhsa_exception_fp_denorm_src 0
		.amdhsa_exception_fp_ieee_div_zero 0
		.amdhsa_exception_fp_ieee_overflow 0
		.amdhsa_exception_fp_ieee_underflow 0
		.amdhsa_exception_fp_ieee_inexact 0
		.amdhsa_exception_int_div_zero 0
	.end_amdhsa_kernel

; __global__ void __launch_bounds__(256, 2) fwd_megakernel(Params p) {
;   cg::grid_group grid = cg::this_grid();
;   __shared__ __attribute__((aligned(16))) unsigned char smem[SMEM_BYTES];
amdhsa.kernels:
  - .agpr_count:     0
    .args:
      - .offset:         0
        .size:           408
        .value_kind:     by_value
      - .offset:         408
        .size:           4
        .value_kind:     hidden_block_count_x
      - .offset:         412
        .size:           4
        .value_kind:     hidden_block_count_y
      - .offset:         416
        .size:           4
        .value_kind:     hidden_block_count_z
      - .offset:         420
        .size:           2
        .value_kind:     hidden_group_size_x
      - .offset:         422
        .size:           2
        .value_kind:     hidden_group_size_y
      - .offset:         424
        .size:           2
        .value_kind:     hidden_group_size_z
      - .offset:         426
        .size:           2
        .value_kind:     hidden_remainder_x
      - .offset:         428
        .size:           2
        .value_kind:     hidden_remainder_y
      - .offset:         430
        .size:           2
        .value_kind:     hidden_remainder_z
      - .offset:         448
        .size:           8
        .value_kind:     hidden_global_offset_x
      - .offset:         456
        .size:           8
        .value_kind:     hidden_global_offset_y
      - .offset:         464
        .size:           8
        .value_kind:     hidden_global_offset_z
      - .offset:         472
        .size:           2
        .value_kind:     hidden_grid_dims
      - .offset:         496
        .size:           8
        .value_kind:     hidden_multigrid_sync_arg
    .group_segment_fixed_size: 58400
    .kernarg_segment_align: 8
    .kernarg_segment_size: 664
    .language:       OpenCL C
    .language_version:
      - 2
      - 0
    .max_flat_workgroup_size: 256
    .name:           _Z14fwd_megakernel6Params
    .private_segment_fixed_size: 0
    .sgpr_count:     104
    .sgpr_spill_count: 125
    .symbol:         _Z14fwd_megakernel6Params.kd
    .uniform_work_group_size: 1
    .uses_dynamic_stack: false
    .vgpr_count:     247
    .vgpr_spill_count: 0
    .wavefront_size: 64
